# NSA sliding-window loop: hand-scheduled path for fully visible blocks (K reads up front, QK/softmax/PV interleaved)
# speedup vs baseline: 1.0023x; 1.0023x over previous
; template <int MODE, bool FX>
; DI void attn_compute(const int lane, const bf16_t* Ks, const bf16_t* Vs, const bf16x8 (&qf)[2][2], AttnSt& st, const float (&invl)[2],
;                      int lo, int hi, float (&impA)[4], float (&impE)[4], const float CL) {
;     ...
;   if (__all(full || none)) {
;     constexpr float L2E = 1.4426950408889634f;
; #pragma unroll
;     for (int hh = 0; hh < 2; ++hh) {
;       float mL;
;       float il = 1.f;
;       if (FX) {
;         mL = full ? CL : 1e30f;
;         if (MODE == 1) il = invl[hh];
;       } else if (MODE != 1) {
;         float mx = -1e30f;
; #pragma unroll
;         for (int kt = 0; kt < 4; ++kt)
; #pragma unroll
;           for (int j = 0; j < 4; ++j) mx = fmaxf(mx, S[kt][hh][j]);
;         mx = full ? mx : -1e30f;
;         mx = fmaxf(mx, shx(mx, 16, lane));
;         mx = fmaxf(mx, shx(mx, 32, lane));
;         const float m_new = fmaxf(st.m[hh], mx);
;         const float alpha = __expf(st.m[hh] - m_new);
;         st.m[hh] = m_new;
;         st.l[hh] *= alpha;
;         if (MODE == 2) {
; #pragma unroll
;           for (int dt = 0; dt < 4; ++dt) st.O[hh][dt] *= alpha;
;         }
;         mL = full ? m_new * L2E : 1e30f;
;       } else {
;         mL = full ? st.m[hh] * L2E : 1e30f;
;         il = invl[hh];
;       }
;       float rs = 0.f;
; #pragma unroll
;       for (int kt = 0; kt < 4; ++kt) {
;         float a = 0.f;
; #pragma unroll
;         for (int j = 0; j < 4; ++j) {
;           float pv = __builtin_amdgcn_exp2f(fmaf(S[kt][hh][j], L2E, -mL));
;           if (MODE == 1) pv *= il;
;           S[kt][hh][j] = pv;
;           a += pv;
;         }
;         rs += a;
;         if (MODE == 1) {
;           impA[kt] += a;
;           impE[kt] += S[kt][hh][3];
;         }
;       }
;       if (MODE != 1 && !(FX && MODE == 2)) st.l[hh] += rs;
;       if (MODE != 0) {
; #pragma unroll
;         for (int c = 0; c < 2; ++c)
;           pf[hh][c] = mk8(pack2(S[2 * c][hh][0], S[2 * c][hh][1]), pack2(S[2 * c][hh][2], S[2 * c][hh][3]),
;                           pack2(S[2 * c + 1][hh][0], S[2 * c + 1][hh][1]), pack2(S[2 * c + 1][hh][2], S[2 * c + 1][hh][3]));
;       }
;     }
;     ...
;   if (MODE != 0) {
; #pragma unroll
;     for (int dt = 0; dt < 4; ++dt) {
;       const int row = dt * 16 + col;
;       const int sw = (row >> 1) & 7;
; #pragma unroll
;       for (int c = 0; c < 2; ++c) {
.Lwin_fast:
	ds_read_b128 v[220:223], v188
	ds_read_b128 v[224:227], v188 offset:2048
	ds_read_b128 v[228:231], v188 offset:4096
	ds_read_b128 v[232:235], v189
	ds_read_b128 v[236:239], v190
	ds_read_b128 v[240:243], v190 offset:2048
	ds_read_b128 v[244:247], v190 offset:4096
	ds_read_b128 v[198:201], v191
	s_waitcnt lgkmcnt(7)
	v_mfma_f32_16x16x32_bf16 v[98:101], v[220:223], v[2:5], 0
	s_waitcnt lgkmcnt(6)
	v_mfma_f32_16x16x32_bf16 v[106:109], v[224:227], v[2:5], 0
	s_waitcnt lgkmcnt(5)
	v_mfma_f32_16x16x32_bf16 v[102:105], v[228:231], v[2:5], 0
	s_waitcnt lgkmcnt(4)
	v_mfma_f32_16x16x32_bf16 v[110:113], v[232:235], v[2:5], 0
	s_waitcnt lgkmcnt(3)
	v_mfma_f32_16x16x32_bf16 v[98:101], v[236:239], v[6:9], v[98:101]
	s_waitcnt lgkmcnt(2)
	v_mfma_f32_16x16x32_bf16 v[106:109], v[240:243], v[6:9], v[106:109]
	s_waitcnt lgkmcnt(1)
	v_mfma_f32_16x16x32_bf16 v[102:105], v[244:247], v[6:9], v[102:105]
	s_waitcnt lgkmcnt(0)
	v_mfma_f32_16x16x32_bf16 v[110:113], v[198:201], v[6:9], v[110:113]
	v_mfma_f32_16x16x32_bf16 v[90:93], v[220:223], v[10:13], 0
	v_mfma_f32_16x16x32_bf16 v[94:97], v[224:227], v[10:13], 0
	v_mfma_f32_16x16x32_bf16 v[82:85], v[228:231], v[10:13], 0
	v_mfma_f32_16x16x32_bf16 v[86:89], v[232:235], v[10:13], 0
	v_fmamk_f32 v74, v98, 0x3fb8aa3b, v205
	v_fmamk_f32 v75, v99, 0x3fb8aa3b, v205
	v_mfma_f32_16x16x32_bf16 v[90:93], v[236:239], v[14:17], v[90:93]
	v_fmamk_f32 v76, v100, 0x3fb8aa3b, v205
	v_fmamk_f32 v77, v101, 0x3fb8aa3b, v205
	v_mfma_f32_16x16x32_bf16 v[94:97], v[240:243], v[14:17], v[94:97]
	v_fmamk_f32 v78, v106, 0x3fb8aa3b, v205
	v_fmamk_f32 v79, v107, 0x3fb8aa3b, v205
	v_mfma_f32_16x16x32_bf16 v[82:85], v[244:247], v[14:17], v[82:85]
	v_fmamk_f32 v80, v108, 0x3fb8aa3b, v205
	v_fmamk_f32 v81, v109, 0x3fb8aa3b, v205
	v_mfma_f32_16x16x32_bf16 v[86:89], v[198:201], v[14:17], v[86:89]
	ds_read_b64 v[220:221], v207 offset:8192
	v_fmamk_f32 v160, v102, 0x3fb8aa3b, v205
	ds_read_b64 v[222:223], v208 offset:8192
	v_fmamk_f32 v161, v103, 0x3fb8aa3b, v205
	ds_read_b64 v[224:225], v209 offset:8192
	v_fmamk_f32 v164, v104, 0x3fb8aa3b, v205
	ds_read_b64 v[226:227], v210 offset:8192
	v_fmamk_f32 v165, v105, 0x3fb8aa3b, v205
	ds_read_b64 v[228:229], v207 offset:10240
	v_fmamk_f32 v166, v110, 0x3fb8aa3b, v205
	ds_read_b64 v[230:231], v208 offset:10240
	v_fmamk_f32 v167, v111, 0x3fb8aa3b, v205
	ds_read_b64 v[232:233], v209 offset:10240
	v_fmamk_f32 v168, v112, 0x3fb8aa3b, v205
	ds_read_b64 v[234:235], v210 offset:10240
	v_fmamk_f32 v169, v113, 0x3fb8aa3b, v205
	ds_read_b64 v[236:237], v207 offset:12288
	v_exp_f32_e32 v74, v74
	ds_read_b64 v[238:239], v208 offset:12288
	v_exp_f32_e32 v75, v75
	ds_read_b64 v[240:241], v209 offset:12288
	v_exp_f32_e32 v76, v76
	ds_read_b64 v[242:243], v210 offset:12288
	v_exp_f32_e32 v77, v77
	ds_read_b64 v[244:245], v211 offset:8192
	v_exp_f32_e32 v78, v78
	ds_read_b64 v[246:247], v212 offset:8192
	v_exp_f32_e32 v79, v79
	ds_read_b64 v[198:199], v213 offset:8192
	v_exp_f32_e32 v80, v80
	ds_read_b64 v[200:201], v214 offset:8192
	v_exp_f32_e32 v81, v81
	v_exp_f32_e32 v160, v160
	v_exp_f32_e32 v161, v161
	v_exp_f32_e32 v164, v164
	v_exp_f32_e32 v165, v165
	v_exp_f32_e32 v166, v166
	v_exp_f32_e32 v167, v167
	v_exp_f32_e32 v168, v168
	v_exp_f32_e32 v169, v169
	v_cvt_pk_bf16_f32 v74, v74, v75
	v_cvt_pk_bf16_f32 v75, v76, v77
	v_cvt_pk_bf16_f32 v76, v78, v79
	v_cvt_pk_bf16_f32 v77, v80, v81
	v_cvt_pk_bf16_f32 v78, v160, v161
	v_cvt_pk_bf16_f32 v79, v164, v165
	v_cvt_pk_bf16_f32 v80, v166, v167
	v_cvt_pk_bf16_f32 v81, v168, v169
	s_waitcnt lgkmcnt(0)
	v_fmamk_f32 v160, v90, 0x3fb8aa3b, v205
	v_fmamk_f32 v161, v91, 0x3fb8aa3b, v205
	v_fmamk_f32 v164, v92, 0x3fb8aa3b, v205
	v_mfma_f32_16x16x32_bf16 v[46:49], v[220:223], v[74:77], v[46:49]
	v_fmamk_f32 v165, v93, 0x3fb8aa3b, v205
	s_mov_b32 s10, s8
	s_mov_b32 s11, s8
	s_mov_b32 s9, s8
	v_mfma_f32_16x16x32_bf16 v[42:45], v[228:231], v[74:77], v[42:45]
	v_mov_b64_e32 v[92:93], s[10:11]
	v_mov_b64_e32 v[90:91], s[8:9]
	v_fmamk_f32 v166, v94, 0x3fb8aa3b, v205
	v_fmamk_f32 v167, v95, 0x3fb8aa3b, v205
	v_mfma_f32_16x16x32_bf16 v[38:41], v[236:239], v[74:77], v[38:41]
	v_fmamk_f32 v168, v96, 0x3fb8aa3b, v205
	v_fmamk_f32 v169, v97, 0x3fb8aa3b, v205
	v_fmamk_f32 v170, v82, 0x3fb8aa3b, v205
	v_fmamk_f32 v171, v83, 0x3fb8aa3b, v205
	v_mfma_f32_16x16x32_bf16 v[34:37], v[244:247], v[74:77], v[34:37]
	v_fmamk_f32 v172, v84, 0x3fb8aa3b, v205
	v_fmamk_f32 v173, v85, 0x3fb8aa3b, v205
	v_fmamk_f32 v174, v86, 0x3fb8aa3b, v205
	v_fmamk_f32 v175, v87, 0x3fb8aa3b, v205
	v_mfma_f32_16x16x32_bf16 v[46:49], v[224:227], v[78:81], v[46:49]
	v_fmamk_f32 v176, v88, 0x3fb8aa3b, v205
	v_fmamk_f32 v177, v89, 0x3fb8aa3b, v205
	v_exp_f32_e32 v160, v160
	v_exp_f32_e32 v161, v161
	v_mfma_f32_16x16x32_bf16 v[42:45], v[232:235], v[78:81], v[42:45]
	v_exp_f32_e32 v164, v164
	v_exp_f32_e32 v165, v165
	v_exp_f32_e32 v166, v166
	v_exp_f32_e32 v167, v167
	v_mfma_f32_16x16x32_bf16 v[38:41], v[240:243], v[78:81], v[38:41]
	v_exp_f32_e32 v168, v168
	v_exp_f32_e32 v169, v169
	v_exp_f32_e32 v170, v170
	v_exp_f32_e32 v171, v171
	v_mfma_f32_16x16x32_bf16 v[34:37], v[198:201], v[78:81], v[34:37]
	v_exp_f32_e32 v172, v172
	v_exp_f32_e32 v173, v173
	v_exp_f32_e32 v174, v174
	v_exp_f32_e32 v175, v175
	v_mfma_f32_16x16x32_bf16 v[54:57], v[90:93], v[74:77], v[54:57]
	v_exp_f32_e32 v176, v176
	v_exp_f32_e32 v177, v177
	v_cvt_pk_bf16_f32 v82, v160, v161
	v_cvt_pk_bf16_f32 v83, v164, v165
	v_mfma_f32_16x16x32_bf16 v[54:57], v[90:93], v[78:81], v[54:57]
	v_cvt_pk_bf16_f32 v84, v166, v167
	v_cvt_pk_bf16_f32 v85, v168, v169
	v_cvt_pk_bf16_f32 v86, v170, v171
	v_cvt_pk_bf16_f32 v87, v172, v173
	v_cvt_pk_bf16_f32 v88, v174, v175
	v_cvt_pk_bf16_f32 v89, v176, v177
	s_nop 1
	v_mfma_f32_16x16x32_bf16 v[30:33], v[220:223], v[82:85], v[30:33]
	v_mfma_f32_16x16x32_bf16 v[26:29], v[228:231], v[82:85], v[26:29]
	v_mfma_f32_16x16x32_bf16 v[22:25], v[236:239], v[82:85], v[22:25]
	v_mfma_f32_16x16x32_bf16 v[18:21], v[244:247], v[82:85], v[18:21]
	v_mfma_f32_16x16x32_bf16 v[30:33], v[224:227], v[86:89], v[30:33]
	v_mfma_f32_16x16x32_bf16 v[26:29], v[232:235], v[86:89], v[26:29]
	v_mfma_f32_16x16x32_bf16 v[22:25], v[240:243], v[86:89], v[22:25]
	v_mfma_f32_16x16x32_bf16 v[18:21], v[198:201], v[86:89], v[18:21]
	v_mfma_f32_16x16x32_bf16 v[50:53], v[90:93], v[82:85], v[50:53]
	v_mfma_f32_16x16x32_bf16 v[50:53], v[90:93], v[86:89], v[50:53]
	s_add_i32 s28, s28, 64
	s_add_i32 s71, s71, 1
	v_subrev_u32_e32 v178, 64, v178
	s_cmp_ge_u32 s72, s25
	s_cbranch_scc1 .LBB0_687
	s_branch .LBB0_681

; DI f32x4 mfma16(bf16x8 a, bf16x8 b, f32x4 c) { return __builtin_amdgcn_mfma_f32_16x16x32_bf16(a, b, c, 0, 0, 0); }
; template <int MODE, bool FX>
; DI void attn_compute(const int lane, const bf16_t* Ks, const bf16_t* Vs, const bf16x8 (&qf)[2][2], AttnSt& st, const float (&invl)[2],
;                      int lo, int hi, float (&impA)[4], float (&impE)[4], const float CL) {
;     ...
;   for (int ks = 0; ks < 2; ++ks) {
; #pragma unroll
;     for (int kt = 0; kt < 4; ++kt) {
;       int row = kt * 16 + col;
;       bf16x8 kf = *(const bf16x8*)(Ks + row * 64 + (((ks * 4 + quad) ^ ((row >> 1) & 7)) << 3));
; #pragma unroll
;       for (int hh = 0; hh < 2; ++hh) S[kt][hh] = mfma16(kf, qf[hh][ks], S[kt][hh]);
;     }
;   }
;   bf16x8 pf[2][2];
;   const bool full = (lo <= 0) && (hi >= 63);
;   const bool none = (hi < 0) || (lo > 63) || (hi < lo);
;   if (__all(full || none)) {
; template <bool FX>
; DI void nsa_tile(const Params& p, int b, int g, int tile, bf16_t* lds, const float CL) {
;     ...
;       for (int s = s0; s <= cur; ++s) {
;         __syncthreads();
;         tile64_sstore(tid, Ks, rk0, rk1);
;         tile64_sstore(tid, Vs, rv0, rv1);
;         __syncthreads();
;         if (s < cur) {
;           tile64_gload(tid, rk0, rk1, kb + (size_t)(s + 1) * 64 * ZS, ZS);
;           tile64_gload(tid, rv0, rv1, vwT + (s + 1) * 64, TS);
;         }
;         attn_compute<2, FX>(lane, Ks, Vs, qf, st, invl, tok - 511 - s * 64, tok - s * 64, dA, dE, CL);
.LBB0_683:
	v_add_u32_e32 v179, 0xfffffe01, v178
	v_cmp_gt_i32_e32 vcc, 1, v179
	v_cmp_lt_i32_e64 s[2:3], 62, v178
	s_and_b64 vcc, vcc, s[2:3]
	s_cmp_eq_u64 vcc, exec
	s_cbranch_scc1 .Lwin_fast
	ds_read_b128 v[90:93], v188 offset:4096
	ds_read_b128 v[74:77], v188
	ds_read_b128 v[82:85], v188 offset:2048
	v_add_u32_e32 v179, 0xfffffe01, v178
	v_cmp_gt_i32_e32 vcc, 1, v179
	v_cmp_lt_i32_e64 s[2:3], 62, v178
	s_and_b64 s[40:41], vcc, s[2:3]
	v_cmp_gt_i32_e32 vcc, 0, v178
	v_cmp_lt_i32_e64 s[2:3], 63, v179
	s_waitcnt lgkmcnt(2)
	v_mfma_f32_16x16x32_bf16 v[102:105], v[90:93], v[2:5], 0
	s_or_b64 s[2:3], s[2:3], vcc
	s_or_b64 s[2:3], s[40:41], s[2:3]
	v_mfma_f32_16x16x32_bf16 v[110:113], v[90:93], v[10:13], 0
	ds_read_b128 v[90:93], v189
	s_waitcnt lgkmcnt(2)
	v_mfma_f32_16x16x32_bf16 v[78:81], v[74:77], v[2:5], 0
	s_waitcnt lgkmcnt(0)
	v_mfma_f32_16x16x32_bf16 v[164:167], v[90:93], v[2:5], 0
	v_mfma_f32_16x16x32_bf16 v[168:171], v[90:93], v[10:13], 0
	ds_read_b128 v[90:93], v190
	v_mfma_f32_16x16x32_bf16 v[74:77], v[74:77], v[10:13], 0
	s_waitcnt lgkmcnt(0)
	v_mfma_f32_16x16x32_bf16 v[98:101], v[90:93], v[6:9], v[78:81]
	v_mfma_f32_16x16x32_bf16 v[90:93], v[90:93], v[14:17], v[74:77]
	s_nop 4
	ds_read_b128 v[74:77], v190 offset:2048
	v_mfma_f32_16x16x32_bf16 v[86:89], v[82:85], v[2:5], 0
	v_mfma_f32_16x16x32_bf16 v[82:85], v[82:85], v[10:13], 0
	s_waitcnt lgkmcnt(0)
	v_mfma_f32_16x16x32_bf16 v[106:109], v[74:77], v[6:9], v[86:89]
	v_mfma_f32_16x16x32_bf16 v[94:97], v[74:77], v[14:17], v[82:85]
	ds_read_b128 v[74:77], v190 offset:4096
	s_waitcnt lgkmcnt(0)
	v_mfma_f32_16x16x32_bf16 v[102:105], v[74:77], v[6:9], v[102:105]
	v_mfma_f32_16x16x32_bf16 v[82:85], v[74:77], v[14:17], v[110:113]
	ds_read_b128 v[74:77], v191
	s_waitcnt lgkmcnt(0)
	v_mfma_f32_16x16x32_bf16 v[110:113], v[74:77], v[6:9], v[164:167]
	v_mfma_f32_16x16x32_bf16 v[86:89], v[74:77], v[14:17], v[168:171]
	v_cndmask_b32_e64 v74, 0, 1, s[2:3]
	v_cmp_ne_u32_e32 vcc, 0, v74
	s_mov_b64 s[2:3], -1
	s_cmp_eq_u64 vcc, exec
	s_cbranch_scc1 .LBB0_685
; template <int MODE, bool FX>
; DI void attn_compute(const int lane, const bf16_t* Ks, const bf16_t* Vs, const bf16x8 (&qf)[2][2], AttnSt& st, const float (&invl)[2],
;                      int lo, int hi, float (&impA)[4], float (&impE)[4], const float CL) {
;     ...
; #pragma unroll
;   for (int hh = 0; hh < 2; ++hh) {
;     if (FX) {
;       constexpr float L2E = 1.4426950408889634f;
;       const float il = (MODE == 1) ? invl[hh] : 1.f;
;       float rs = 0.f;
; #pragma unroll
;       for (int kt = 0; kt < 4; ++kt) {
;         float a = 0.f;
; #pragma unroll
;         for (int j = 0; j < 4; ++j) {
;           const int kl = kt * 16 + quad * 4 + j;
;           const bool v = (kl >= lo) && (kl <= hi);
;           float pv = v ? __builtin_amdgcn_exp2f(fmaf(S[kt][hh][j], L2E, -CL)) : 0.f;
;           if (MODE == 1) pv *= il;
;           S[kt][hh][j] = pv;
;           a += pv;
;         }
;         rs += a;
;         if (MODE == 1) {
;           impA[kt] += a;
;           impE[kt] += S[kt][hh][3];
;         }
;       }
;       if (MODE != 1 && !(FX && MODE == 2)) st.l[hh] += rs;
;       if (MODE != 0) {
; #pragma unroll
;         for (int c = 0; c < 2; ++c)
;           pf[hh][c] = mk8(pack2(S[2 * c][hh][0], S[2 * c][hh][1]), pack2(S[2 * c][hh][2], S[2 * c][hh][3]),
;                           pack2(S[2 * c + 1][hh][0], S[2 * c + 1][hh][1]), pack2(S[2 * c + 1][hh][2], S[2 * c + 1][hh][3]));
;       }
	v_cmp_ge_i32_e32 vcc, v118, v179
	v_cmp_le_i32_e64 s[2:3], v118, v178
	s_and_b64 vcc, vcc, s[2:3]
	v_cmp_ge_i32_e64 s[2:3], v184, v179
	v_cmp_lt_i32_e64 s[4:5], v118, v178
	s_and_b64 s[2:3], s[2:3], s[4:5]
	v_cmp_ge_i32_e64 s[4:5], v119, v179
	v_cmp_le_i32_e64 s[6:7], v119, v178
	s_and_b64 s[44:45], s[4:5], s[6:7]
	v_cmp_ge_i32_e64 s[4:5], v192, v179
	v_cmp_le_i32_e64 s[6:7], v192, v178
	s_and_b64 s[48:49], s[4:5], s[6:7]
	v_cmp_ge_i32_e64 s[4:5], v120, v179
	v_cmp_le_i32_e64 s[6:7], v120, v178
	s_and_b64 s[42:43], s[4:5], s[6:7]
	v_cmp_ge_i32_e64 s[4:5], v193, v179
	v_cmp_le_i32_e64 s[6:7], v193, v178
	s_and_b64 s[46:47], s[4:5], s[6:7]
	v_cmp_ge_i32_e64 s[4:5], v122, v179
	v_cmp_le_i32_e64 s[6:7], v122, v178
	s_and_b64 s[52:53], s[4:5], s[6:7]
	v_cmp_ge_i32_e64 s[4:5], v121, v179
	v_cmp_le_i32_e64 s[6:7], v121, v178
	s_and_b64 s[56:57], s[4:5], s[6:7]
	v_cmp_ge_i32_e64 s[4:5], v194, v179
	v_cmp_le_i32_e64 s[6:7], v194, v178
	s_and_b64 s[50:51], s[4:5], s[6:7]
	v_cmp_ge_i32_e64 s[4:5], v195, v179
	v_cmp_le_i32_e64 s[6:7], v195, v178
	s_and_b64 s[54:55], s[4:5], s[6:7]
	v_cmp_ge_i32_e64 s[4:5], v206, v179
	v_cmp_le_i32_e64 s[6:7], v206, v178
	s_and_b64 s[60:61], s[4:5], s[6:7]
	v_cmp_ge_i32_e64 s[4:5], v124, v179
	v_cmp_le_i32_e64 s[6:7], v124, v178
	v_fmamk_f32 v74, v98, 0x3fb8aa3b, v205
	v_fmamk_f32 v75, v99, 0x3fb8aa3b, v205
	v_fmamk_f32 v76, v100, 0x3fb8aa3b, v205
	v_fmamk_f32 v77, v101, 0x3fb8aa3b, v205
	v_fmamk_f32 v78, v106, 0x3fb8aa3b, v205
	v_fmamk_f32 v79, v107, 0x3fb8aa3b, v205
	v_fmamk_f32 v80, v108, 0x3fb8aa3b, v205
	v_fmamk_f32 v81, v109, 0x3fb8aa3b, v205
	v_fmamk_f32 v160, v102, 0x3fb8aa3b, v205
	v_fmamk_f32 v161, v103, 0x3fb8aa3b, v205
	v_fmamk_f32 v164, v104, 0x3fb8aa3b, v205
	v_fmamk_f32 v165, v105, 0x3fb8aa3b, v205
	s_and_b64 s[64:65], s[4:5], s[6:7]
	v_fmamk_f32 v166, v110, 0x3fb8aa3b, v205
	v_cmp_ge_i32_e64 s[4:5], v126, v179
	v_cmp_le_i32_e64 s[6:7], v126, v178
	v_fmamk_f32 v167, v111, 0x3fb8aa3b, v205
	v_fmamk_f32 v168, v112, 0x3fb8aa3b, v205
	v_fmamk_f32 v169, v113, 0x3fb8aa3b, v205
	v_exp_f32_e32 v74, v74
	v_exp_f32_e32 v75, v75
	v_exp_f32_e32 v76, v76
	v_exp_f32_e32 v77, v77
	v_exp_f32_e32 v78, v78
	v_exp_f32_e32 v79, v79
	v_exp_f32_e32 v80, v80
	v_exp_f32_e32 v81, v81
	v_exp_f32_e32 v160, v160
	v_exp_f32_e32 v161, v161
	v_exp_f32_e32 v164, v164
	v_exp_f32_e32 v165, v165
	v_exp_f32_e32 v166, v166
	s_and_b64 s[58:59], s[4:5], s[6:7]
	v_exp_f32_e32 v167, v167
	v_cmp_ge_i32_e64 s[4:5], v123, v179
	v_cmp_le_i32_e64 s[6:7], v123, v178
	v_exp_f32_e32 v168, v168
	v_exp_f32_e32 v169, v169
	s_and_b64 s[62:63], s[4:5], s[6:7]
	v_cmp_ge_i32_e64 s[4:5], v125, v179
	v_cmp_le_i32_e64 s[6:7], v125, v178
	s_and_b64 s[66:67], s[4:5], s[6:7]
	v_cmp_ge_i32_e64 s[4:5], v127, v179
	v_cmp_le_i32_e64 s[6:7], v127, v178
	s_and_b64 s[68:69], s[4:5], s[6:7]
	v_cndmask_b32_e32 v74, 0, v74, vcc
	v_cndmask_b32_e64 v75, 0, v75, s[2:3]
	v_cndmask_b32_e64 v76, 0, v76, s[44:45]
	v_cndmask_b32_e64 v77, 0, v77, s[48:49]
	v_cndmask_b32_e64 v78, 0, v78, s[42:43]
	v_cndmask_b32_e64 v79, 0, v79, s[46:47]
	v_cndmask_b32_e64 v80, 0, v80, s[52:53]
	v_cndmask_b32_e64 v81, 0, v81, s[56:57]
	v_cndmask_b32_e64 v160, 0, v160, s[50:51]
	v_cndmask_b32_e64 v161, 0, v161, s[54:55]
	v_cndmask_b32_e64 v164, 0, v164, s[60:61]
	v_cndmask_b32_e64 v165, 0, v165, s[64:65]
	v_cndmask_b32_e64 v166, 0, v166, s[58:59]
	v_cndmask_b32_e64 v167, 0, v167, s[62:63]
	v_cndmask_b32_e64 v168, 0, v168, s[66:67]
	v_cndmask_b32_e64 v169, 0, v169, s[68:69]
	v_cvt_pk_bf16_f32 v74, v74, v75
	v_cvt_pk_bf16_f32 v75, v76, v77
	v_cvt_pk_bf16_f32 v76, v78, v79
	v_cvt_pk_bf16_f32 v77, v80, v81
	v_cvt_pk_bf16_f32 v78, v160, v161
	v_cvt_pk_bf16_f32 v79, v164, v165
	v_cvt_pk_bf16_f32 v80, v166, v167
	v_cvt_pk_bf16_f32 v81, v168, v169
	v_fmamk_f32 v160, v90, 0x3fb8aa3b, v205
	v_fmamk_f32 v161, v91, 0x3fb8aa3b, v205
	v_fmamk_f32 v164, v92, 0x3fb8aa3b, v205
	v_fmamk_f32 v165, v93, 0x3fb8aa3b, v205
	v_fmamk_f32 v166, v94, 0x3fb8aa3b, v205
	v_fmamk_f32 v167, v95, 0x3fb8aa3b, v205
	v_fmamk_f32 v168, v96, 0x3fb8aa3b, v205
	v_fmamk_f32 v169, v97, 0x3fb8aa3b, v205
	v_fmamk_f32 v170, v82, 0x3fb8aa3b, v205
	v_fmamk_f32 v171, v83, 0x3fb8aa3b, v205
	v_fmamk_f32 v172, v84, 0x3fb8aa3b, v205
	v_fmamk_f32 v173, v85, 0x3fb8aa3b, v205
	v_fmamk_f32 v174, v86, 0x3fb8aa3b, v205
	v_fmamk_f32 v175, v87, 0x3fb8aa3b, v205
	v_fmamk_f32 v176, v88, 0x3fb8aa3b, v205
	v_fmamk_f32 v177, v89, 0x3fb8aa3b, v205
	v_exp_f32_e32 v160, v160
	v_exp_f32_e32 v161, v161
	v_exp_f32_e32 v164, v164
	v_exp_f32_e32 v165, v165
	v_exp_f32_e32 v166, v166
	v_exp_f32_e32 v167, v167
	v_exp_f32_e32 v168, v168
	v_exp_f32_e32 v169, v169
	v_exp_f32_e32 v170, v170
	v_exp_f32_e32 v171, v171
	v_exp_f32_e32 v172, v172
	v_exp_f32_e32 v173, v173
	v_exp_f32_e32 v174, v174
	v_exp_f32_e32 v175, v175
	v_exp_f32_e32 v176, v176
	v_exp_f32_e32 v177, v177
	v_cndmask_b32_e32 v160, 0, v160, vcc
	v_cndmask_b32_e64 v161, 0, v161, s[2:3]
	v_cndmask_b32_e64 v164, 0, v164, s[44:45]
	v_cndmask_b32_e64 v165, 0, v165, s[48:49]
	v_cndmask_b32_e64 v166, 0, v166, s[42:43]
	v_cndmask_b32_e64 v167, 0, v167, s[46:47]
	v_cndmask_b32_e64 v168, 0, v168, s[52:53]
	v_cndmask_b32_e64 v169, 0, v169, s[56:57]
	v_cndmask_b32_e64 v170, 0, v170, s[50:51]
	v_cndmask_b32_e64 v171, 0, v171, s[54:55]
	v_cndmask_b32_e64 v172, 0, v172, s[60:61]
	v_cndmask_b32_e64 v173, 0, v173, s[64:65]
	v_cndmask_b32_e64 v174, 0, v174, s[58:59]
	v_cndmask_b32_e64 v175, 0, v175, s[62:63]
	v_cndmask_b32_e64 v176, 0, v176, s[66:67]
	v_cndmask_b32_e64 v177, 0, v177, s[68:69]
	s_mov_b64 s[2:3], 0
